# pointer-table entries of 4 more inputs kept in spare v255 lanes (30 of 51 LDS pointer re-reads removed)
# baseline (speedup 1.0000x reference)
; #define FRESH() do { tid = threadIdx.x; asm volatile("" : "+v"(tid)); lane = tid & 63; wave = __builtin_amdgcn_readfirstlane(tid >> 6); } while (0)
; #define GRIDBAR() do { XcdBarrier b_; b_.bar = (unsigned*)kp.ws() + 1024; b_.x = xb_xcc_id(); b_.st = (volatile LAS unsigned*)(lds + CTRL_OFF) + 8; xcd_barrier(b_); } while (0)
;     __device__ __forceinline__ unsigned long long ld(int i) const { const unsigned long long v = *(const volatile __attribute__((address_space(3))) unsigned long long*)(unsigned)(PTAB_OFF + 8 * i);
;         const unsigned lo = __builtin_amdgcn_readfirstlane((unsigned)v), hi = __builtin_amdgcn_readfirstlane((unsigned)(v >> 32)); return ((unsigned long long)hi << 32) | lo; }
;     __device__ __forceinline__ const float* in(int i) const { return (const float*)(const __attribute__((address_space(1))) float*)ld(i); }
;     __device__ __forceinline__ float* out() const { return (float*)(__attribute__((address_space(1))) float*)ld(22); }
;     __device__ __forceinline__ unsigned char* ws() const { return (unsigned char*)(__attribute__((address_space(1))) unsigned char*)ld(23); }
; __global__ void __launch_bounds__(512, 2) fwd_kernel(KP kparg) {
;     ...
;     for (int l = 0; l < 2; ++l) {
;         const float* mod = (const float*)(ws + WS_MOD) + (size_t)l * 5 * 6144;
;         const float* xin = l ? kp.out() : kp.in(I_X); const float* cin = l ? CTXB : kp.in(I_CTX);
;         FRESH();
;     ...
;         if (l == 0) { prologue<1>(kp, lds, tid, lane, wave); }
;     ...
;         for (int rep = 0; rep < REP_NORM; ++rep)
;         norm_pass(xin, cin, H, kp.in(I_N1G) + l * D, mod, 0, 1024, MALL, lane, wave, l ? (const float*)(ws + WS_PART) : nullptr, CTXB);
;         GRIDBAR();
;         { pg8::Gemm g{H, (const bf16*)(ws + WS_WIN) + (size_t)l * INP * D, MALL, INP, D}; pg8::StaticOrder S; S.init(MALL, INP, G, c);
;           pg8::EpiBf16S E{Pm, INP};
;     ...
;           for (int rep = 0; rep < REP_GEMM; ++rep)
;           pg8::gemm_phase<pg8::EpiBf16S, pg8::StaticOrder, true, true>(ldsg, g, S, E);
;     ...
;         }
;         GRIDBAR();
;         FRESH();
;         v4u gz0 = {0u, 0u, 0u, 0u}, gz1 = gz0, gw0 = gz0, gw1 = gz0; { const int i0 = (G == 256) ? XITEM(c) : c; if (i0 < 1056) gla_prefetch(gz0, gz1, gw0, gw1, kp, l, i0, lane, wave); }
.LBB0_77:
	s_or_b64 exec, exec, s[0:1]
	s_add_u32 s90, s46, 0x3400000
	s_addc_u32 s91, s33, 0
	s_add_u32 s92, s46, 0x7800000
	s_addc_u32 s93, s33, 0
	s_add_u32 s81, s46, 0x10e00000
	s_addc_u32 s85, s33, 0
	s_add_u32 s14, s46, 0x12c00000
	s_addc_u32 s15, s33, 0
	s_add_u32 s94, s46, 0x3000000
	s_addc_u32 s95, s33, 0
	s_add_u32 s0, s46, 0x100000
	v_writelane_b32 v253, s0, 3
	s_addc_u32 s0, s33, 0
	v_writelane_b32 v253, s0, 4
	s_lshl_b32 s0, s73, 3
	s_lshl_b32 s52, s84, 3
	s_add_u32 s50, s46, 0x1e400000
	s_addc_u32 s51, s33, 0
	v_writelane_b32 v253, s0, 5
	s_add_u32 s0, s46, 0x200000
	v_writelane_b32 v253, s0, 6
	s_addc_u32 s0, s33, 0
	s_cmpk_lt_i32 s73, 0x4a4
	v_writelane_b32 v253, s0, 7
	s_cselect_b64 s[0:1], -1, 0
	v_writelane_b32 v253, s0, 8
	s_ashr_i32 s86, s73, 31
	s_ashr_i32 s2, s73, 3
	v_writelane_b32 v253, s1, 9
	s_lshr_b32 s0, s86, 29
	s_add_i32 s0, s73, s0
	s_ashr_i32 s13, s0, 3
	s_and_b32 s0, s0, -8
	s_sub_i32 s16, s73, s0
	s_mul_i32 s0, s16, 0x94
	s_lshl_b32 s1, s73, 5
	s_add_i32 s6, s0, 4
	s_and_b32 s0, s73, 0xffffff00
	v_writelane_b32 v253, s1, 10
	s_and_b32 s1, s1, 0xe0
	s_add_i32 s0, s2, s0
	s_add_i32 s54, s1, s2
	s_ashr_i32 s89, s84, 31
	s_add_i32 s3, s0, s1
	s_sub_i32 s2, s54, 32
	s_cmp_lt_i32 s73, 16
	s_cselect_b32 s4, s73, -1
	s_cmpk_eq_i32 s84, 0x100
	s_cselect_b64 s[56:57], -1, 0
	s_and_b64 s[0:1], s[56:57], exec
	s_cselect_b32 s1, s3, s73
	s_cselect_b32 s0, s2, s4
	s_cmpk_lt_i32 s1, 0x420
	s_cselect_b64 s[2:3], -1, 0
	v_writelane_b32 v253, s2, 11
	s_mov_b32 s79, 0
	v_writelane_b32 v254, s16, 0
	v_writelane_b32 v253, s3, 12
	v_writelane_b32 v253, s1, 13
	s_lshl_b32 s1, s1, 1
	s_cmpk_lt_i32 s73, 0x72f
	v_writelane_b32 v253, s1, 14
	s_cselect_b64 s[2:3], -1, 0
	v_writelane_b32 v253, s2, 15
	s_add_i32 s1, s54, 0x100
	s_cmpk_lt_i32 s73, 0x200
	v_writelane_b32 v253, s3, 16
	v_writelane_b32 v253, s1, 17
	s_cselect_b64 s[2:3], -1, 0
	v_writelane_b32 v253, s2, 18
	s_cmp_lt_u32 s0, 16
	v_mov_b32_e32 v35, 0
	v_writelane_b32 v253, s3, 19
	s_cselect_b64 s[2:3], -1, 0
	v_writelane_b32 v253, s2, 20
	s_lshl_b32 s1, s0, 6
	v_mov_b32_e32 v217, 0x264b0
	v_writelane_b32 v253, s3, 21
	s_and_b32 s2, s1, 0x300
	s_and_b32 s1, s1, 0x380
	s_bitset1_b32 s1, 15
	v_writelane_b32 v253, s1, 22
	s_and_b32 s1, s0, 1
	s_lshl_b32 s0, s1, 6
	s_or_b32 s3, s2, 0x8000
	s_or_b32 s2, s2, 0x8080
	v_writelane_b32 v253, s3, 23
	s_add_u32 s3, s46, 0xb00000
	s_addc_u32 s4, s33, 0
	s_lshl_b32 s7, s16, 6
	s_cmp_lt_i32 s73, 64
	v_writelane_b32 v253, s2, 24
	s_cselect_b64 s[8:9], -1, 0
	s_and_b32 s18, s73, 3
	v_writelane_b32 v253, s8, 25
	s_lshl_b32 s2, s18, 9
	v_mov_b32_e32 v204, 0x264b8
	v_mov_b32_e32 v162, 0x264b8
	ds_read_b64 v[160:161], v162
	s_waitcnt lgkmcnt(0)
	v_readfirstlane_b32 s100, v160
	v_readfirstlane_b32 s101, v161
	s_nop 3
	v_writelane_b32 v255, s100, 62
	v_writelane_b32 v255, s101, 63
	v_mov_b32_e32 v162, 0x26440
	ds_read_b64 v[160:161], v162
	s_waitcnt lgkmcnt(0)
	v_readfirstlane_b32 s100, v160
	v_readfirstlane_b32 s101, v161
	s_nop 3
	v_writelane_b32 v255, s100, 60
	v_writelane_b32 v255, s101, 61
	v_mov_b32_e32 v162, 0x26448
	ds_read_b64 v[160:161], v162
	s_waitcnt lgkmcnt(0)
	v_readfirstlane_b32 s100, v160
	v_readfirstlane_b32 s101, v161
	s_nop 3
	v_writelane_b32 v255, s100, 58
	v_writelane_b32 v255, s101, 59
	v_mov_b32_e32 v162, 0x26468
	ds_read_b64 v[160:161], v162
	s_waitcnt lgkmcnt(0)
	v_readfirstlane_b32 s100, v160
	v_readfirstlane_b32 s101, v161
	s_nop 3
	v_writelane_b32 v255, s100, 56
	v_writelane_b32 v255, s101, 57
	v_mov_b32_e32 v162, 0x264b0
	ds_read_b64 v[160:161], v162
	s_waitcnt lgkmcnt(0)
	v_readfirstlane_b32 s100, v160
	v_readfirstlane_b32 s101, v161
	s_nop 3
	v_writelane_b32 v255, s100, 54
	v_writelane_b32 v255, s101, 55
	v_writelane_b32 v253, s9, 26
	s_add_u32 s8, s46, s2
	s_addc_u32 s9, s33, 0
	s_add_u32 s10, s3, s2
	v_writelane_b32 v253, s3, 27
	s_addc_u32 s11, s4, 0
	s_ashr_i32 s2, s73, 4
	s_bfe_u32 s12, s73, 0x20002
	s_lshl_b32 s3, s18, 22
	v_writelane_b32 v253, s4, 28
	s_add_u32 s4, s50, s3
	s_addc_u32 s5, s51, 0
	v_writelane_b32 v253, s4, 29
	s_ashr_i32 s3, s2, 31
	v_mov_b32_e32 v205, 0x358637bd
	v_writelane_b32 v253, s5, 30
	s_lshl_b64 s[4:5], s[2:3], 19
	s_lshl_b32 s3, s12, 19
	s_add_u32 s60, s10, s3
	s_addc_u32 s61, s11, 0
	s_add_u32 s10, s60, 0x40000
	s_addc_u32 s11, s61, 0
	s_add_u32 s3, s8, s4
	s_addc_u32 s4, s9, s5
	s_add_u32 s62, s3, 0x14e00000
	s_addc_u32 s63, s4, 0
	s_add_u32 s64, s3, 0x14e40000
	s_addc_u32 s65, s4, 0
	v_writelane_b32 v253, s10, 31
	s_add_u32 s4, s60, 0x40080
	s_addc_u32 s5, s61, 0
	v_writelane_b32 v253, s11, 32
	v_writelane_b32 v253, s4, 33
	s_lshl_b32 s3, s12, 8
	s_mul_i32 s12, s12, 0x160000
	v_writelane_b32 v253, s5, 34
	s_lshl_b32 s4, s2, 8
	v_writelane_b32 v253, s3, 35
	s_or_b32 s3, s4, 16
	v_writelane_b32 v253, s3, 36
	s_or_b32 s5, s4, 32
	v_writelane_b32 v253, s5, 37
	s_or_b32 s5, s4, 48
	v_writelane_b32 v253, s5, 38
	s_or_b32 s5, s4, 0x80
	v_writelane_b32 v253, s5, 39
	s_or_b32 s5, s4, 0x90
	v_writelane_b32 v253, s5, 40
	s_or_b32 s5, s4, 0xa0
	v_writelane_b32 v253, s5, 41
	v_writelane_b32 v253, s4, 42
	s_or_b32 s4, s4, 0xb0
	v_writelane_b32 v253, s4, 43
	s_add_u32 s4, s46, 0xf00000
	v_writelane_b32 v253, s4, 44
	s_addc_u32 s4, s33, 0
	v_writelane_b32 v253, s4, 45
	s_add_u32 s5, s46, 0x2500000
	s_mov_b32 s4, s18
	s_addc_u32 s8, s33, 0
	v_writelane_b32 v253, s4, 46
	s_cmp_eq_u32 s18, 2
	s_mul_hi_i32 s3, s2, 0x160000
	v_writelane_b32 v253, s5, 47
	s_movk_i32 s4, 0x600
	s_cselect_b32 s4, s4, 0x880
	v_writelane_b32 v253, s4, 48
	s_mul_i32 s2, s2, 0x160000
	v_mov_b32_e32 v206, 0x260
	v_writelane_b32 v253, s5, 49
	s_lshl_b32 s4, s73, 6
;     __device__ __forceinline__ const float* in(int i) const { return (const float*)(const __attribute__((address_space(1))) float*)ld(i); }
;     __device__ __forceinline__ float* out() const { return (float*)(__attribute__((address_space(1))) float*)ld(22); }
;     __device__ __forceinline__ unsigned char* ws() const { return (unsigned char*)(__attribute__((address_space(1))) unsigned char*)ld(23); }
; #define FRESH() do { tid = threadIdx.x; asm volatile("" : "+v"(tid)); lane = tid & 63; wave = __builtin_amdgcn_readfirstlane(tid >> 6); } while (0)
; #define GRIDBAR() do { XcdBarrier b_; b_.bar = (unsigned*)kp.ws() + 1024; b_.x = xb_xcc_id(); b_.st = (volatile LAS unsigned*)(lds + CTRL_OFF) + 8; xcd_barrier(b_); } while (0)
; __global__ void __launch_bounds__(512, 2) fwd_kernel(KP kparg) {
;     ...
;     for (int l = 0; l < 2; ++l) {
;         const float* mod = (const float*)(ws + WS_MOD) + (size_t)l * 5 * 6144;
;         const float* xin = l ? kp.out() : kp.in(I_X); const float* cin = l ? CTXB : kp.in(I_CTX);
;         FRESH();
;     ...
;         if (l == 0) { prologue<1>(kp, lds, tid, lane, wave); }
;     ...
;         for (int rep = 0; rep < REP_NORM; ++rep)
;         norm_pass(xin, cin, H, kp.in(I_N1G) + l * D, mod, 0, 1024, MALL, lane, wave, l ? (const float*)(ws + WS_PART) : nullptr, CTXB);
;         GRIDBAR();
;         { pg8::Gemm g{H, (const bf16*)(ws + WS_WIN) + (size_t)l * INP * D, MALL, INP, D}; pg8::StaticOrder S; S.init(MALL, INP, G, c);
;           pg8::EpiBf16S E{Pm, INP};
;     ...
;           for (int rep = 0; rep < REP_GEMM; ++rep)
;           pg8::gemm_phase<pg8::EpiBf16S, pg8::StaticOrder, true, true>(ldsg, g, S, E);
;     ...
;         }
;         GRIDBAR();
;         FRESH();
;         v4u gz0 = {0u, 0u, 0u, 0u}, gz1 = gz0, gw0 = gz0, gw1 = gz0; { const int i0 = (G == 256) ? XITEM(c) : c; if (i0 < 1056) gla_prefetch(gz0, gz1, gw0, gw1, kp, l, i0, lane, wave); }
;         for (int it = c; it < 1056 + 528 + 255; it += G) { const int item = (G == 256) ? XITEM(it) : it; if (item >= 1056 + 528) break;
	s_and_b32 s4, s4, 0x80
	s_sub_i32 s4, 0x300, s4
	s_lshr_b32 s49, s4, 6
	v_writelane_b32 v253, s5, 50
	s_add_u32 s4, s5, s12
	v_writelane_b32 v253, s4, 51
	s_addc_u32 s4, s8, 0
	v_writelane_b32 v253, s8, 52
	s_add_u32 s8, s46, s2
	s_addc_u32 s9, s33, s3
	v_writelane_b32 v253, s4, 53
	s_add_u32 s2, s8, 0x1dc00000
	v_writelane_b32 v253, s2, 54
	s_addc_u32 s2, s9, 0
	s_add_i32 s55, s49, -2
	v_writelane_b32 v253, s2, 55
	s_cmp_lt_i32 s16, 4
	s_mul_i32 s2, s16, 0x95
	s_cselect_b32 s2, s2, s6
	s_add_i32 s2, s2, s13
	s_mul_hi_i32 s3, s2, 0x38e38e39
	s_lshr_b32 s4, s3, 31
	s_ashr_i32 s3, s3, 4
	s_add_i32 s3, s3, s4
	s_mul_i32 s4, s3, 0x48
	s_lshl_b32 s5, s3, 3
	s_sub_i32 s4, s2, s4
	s_sub_i32 s2, 0x84, s5
	s_min_u32 s6, s2, 8
	s_cmp_lt_i32 s16, 0
	s_mul_i32 s2, s16, 0x41
	s_cselect_b32 s2, s2, s7
	s_add_i32 s2, s2, s13
	s_ashr_i32 s3, s2, 31
	s_lshr_b32 s3, s3, 27
	s_add_i32 s3, s2, s3
	s_and_b32 s7, s3, 0xffe0
	s_sub_i32 s2, s2, s7
	s_bfe_i32 s7, s2, 0x80000
	s_bfe_u32 s7, s7, 0x3000c
	s_add_i32 s7, s2, s7
	s_and_b32 s10, s7, 0xf8
	s_sub_i32 s2, s2, s10
	s_ashr_i32 s3, s3, 5
	s_bfe_i32 s7, s7, 0x80000
	s_lshl_b32 s3, s3, 3
	s_sext_i32_i16 s7, s7
	s_sext_i32_i8 s2, s2
	v_writelane_b32 v253, s13, 56
	s_add_i32 s12, s3, s2
	s_ashr_i32 s2, s7, 3
	v_writelane_b32 v253, s2, 57
	s_lshr_b32 s2, s7, 3
	s_bfe_i64 s[2:3], s[2:3], 0x100000
	s_lshl_b64 s[2:3], s[2:3], 19
	s_ashr_i32 s13, s12, 31
	v_writelane_b32 v253, s2, 58
	v_cvt_f32_ubyte0_e32 v2, s6
	s_waitcnt lgkmcnt(0)
	v_cvt_f32_i32_e32 v1, s4
	v_writelane_b32 v253, s3, 59
	s_lshl_b64 s[2:3], s[12:13], 19
	s_add_u32 s2, s81, s2
	s_addc_u32 s3, s85, s3
	s_add_u32 s10, s2, 0x40000
	v_writelane_b32 v253, s2, 60
	s_addc_u32 s11, s3, 0
	v_rcp_iflag_f32_e32 v3, v2
	v_writelane_b32 v253, s3, 61
	v_writelane_b32 v253, s10, 62
	s_lshr_b32 s2, s16, 31
	v_writelane_b32 v254, s2, 1
	v_writelane_b32 v253, s11, 63
	s_mov_b32 s10, s12
	v_writelane_b32 v254, s10, 2
	s_mul_i32 s3, s12, 0x160000
	s_mul_hi_i32 s2, s12, 0x160000
	v_writelane_b32 v254, s11, 3
	s_add_u32 s10, s14, s3
	v_writelane_b32 v254, s14, 4
	s_addc_u32 s11, s15, s2
	s_add_u32 s2, s10, 0xb0000
	v_writelane_b32 v254, s15, 5
	v_writelane_b32 v254, s10, 6
	s_addc_u32 s3, s11, 0
	v_mul_f32_e32 v3, v1, v3
	v_writelane_b32 v254, s11, 7
	v_writelane_b32 v254, s2, 8
	v_trunc_f32_e32 v3, v3
	v_fma_f32 v1, -v3, v2, v1
	v_writelane_b32 v254, s3, 9
	s_ashr_i32 s2, s4, 30
	s_or_b32 s7, s2, 1
	v_cmp_ge_f32_e64 s[2:3], |v1|, v2
	v_cvt_i32_f32_e32 v1, v3
	s_and_b64 s[2:3], s[2:3], exec
	s_cselect_b32 s2, s7, 0
	v_mbcnt_lo_u32_b32 v2, -1, 0
	v_readfirstlane_b32 s3, v1
	s_add_i32 s2, s3, s2
	s_mul_i32 s3, s2, s6
	s_sub_i32 s3, s4, s3
	s_sext_i32_i8 s3, s3
	s_add_i32 s6, s5, s3
	s_bfe_i64 s[4:5], s[2:3], 0x80000
	s_lshl_b64 s[4:5], s[4:5], 19
	v_writelane_b32 v254, s4, 10
	s_ashr_i32 s7, s6, 31
	s_sext_i32_i8 s2, s2
	v_writelane_b32 v254, s5, 11
	s_mov_b32 s4, s6
	v_writelane_b32 v254, s4, 12
	v_mov_b32_e32 v214, 1
	v_mov_b32_e32 v207, 0x26440
	v_writelane_b32 v254, s5, 13
	s_lshl_b64 s[4:5], s[6:7], 19
	s_add_u32 s4, s90, s4
	v_writelane_b32 v254, s2, 14
	s_mul_i32 s2, s1, 3
	s_mulk_i32 s1, 0xc0
	s_addc_u32 s5, s91, s5
	v_writelane_b32 v254, s1, 15
	s_add_u32 s6, s4, 0x40000
	v_writelane_b32 v254, s4, 16
	s_addc_u32 s7, s5, 0
	s_ashr_i32 s53, s52, 31
	v_writelane_b32 v254, s5, 17
	v_writelane_b32 v254, s6, 18
	s_lshl_b32 s59, s84, 5
	s_lshl_b64 s[66:67], s[52:53], 11
	v_writelane_b32 v254, s7, 19
	s_add_u32 s1, s8, 0x1dcb0080
	v_writelane_b32 v254, s1, 20
	s_addc_u32 s1, s9, 0
	v_writelane_b32 v254, s1, 21
	s_lshl_b32 s1, s2, 2
	v_writelane_b32 v254, s1, 22
	s_lshl_b32 s0, s0, 1
	v_writelane_b32 v254, s0, 23
	s_add_i32 s0, 0, 0x26020
	v_writelane_b32 v254, s0, 24
	s_add_i32 s0, 0, 0x26024
	v_writelane_b32 v254, s0, 25
	s_add_i32 s0, 0, 0x22000
	v_writelane_b32 v254, s0, 26
	s_mov_b32 s0, s79
	v_writelane_b32 v254, s0, 27
	v_mov_b32_e32 v252, 0x26448
	v_mov_b32_e32 v215, 0x26468
	v_writelane_b32 v254, s1, 28
	v_writelane_b32 v254, s73, 29
	v_writelane_b32 v254, s76, 30
	s_mov_b32 s0, s80
	v_mov_b32_e32 v70, v35
	v_writelane_b32 v254, s77, 31
	v_writelane_b32 v254, s84, 32
	v_writelane_b32 v254, s0, 33
	v_mov_b32_e32 v71, v35
	v_mov_b32_e32 v72, v35
	v_writelane_b32 v254, s1, 34
	v_writelane_b32 v254, s90, 35
	v_mov_b32_e32 v73, v35
	v_mbcnt_hi_u32_b32 v216, -1, v2
	v_writelane_b32 v254, s91, 36
	v_writelane_b32 v254, s92, 37
	v_mov_b32_e32 v222, 0x41b17218
	v_mov_b32_e32 v223, 0x3fb8aa3b
	v_writelane_b32 v254, s93, 38
	v_writelane_b32 v254, s81, 39
	v_writelane_b32 v254, s85, 40
	v_writelane_b32 v254, s94, 41
	v_mov_b32_e32 v224, 0xf149f2ca
	v_mov_b64_e32 v[0:1], 0x200
	v_writelane_b32 v254, s95, 42
	v_writelane_b32 v254, s52, 43
	s_mov_b32 s68, 0x8080
	s_movk_i32 s69, 0xc0
	v_writelane_b32 v254, s53, 44
	v_writelane_b32 v254, s86, 45
	v_writelane_b32 v254, s89, 46
	v_writelane_b32 v254, s54, 47
	v_writelane_b32 v254, s56, 48
	s_movk_i32 s96, 0x2000
	s_movk_i32 s87, 0x3000
	v_writelane_b32 v254, s57, 49
	v_writelane_b32 v254, s59, 50
	v_writelane_b32 v254, s66, 51
	s_mov_b32 s88, 0xf800000
	s_movk_i32 s33, 0x1200
	v_writelane_b32 v254, s67, 52
	v_writelane_b32 v254, s50, 53
	s_mov_b32 s58, 0xf149f2ca
	s_mov_b64 s[14:15], 0
	v_writelane_b32 v254, s51, 54
	v_writelane_b32 v254, s60, 55
	s_mov_b64 s[46:47], -1
	s_mov_b64 s[70:71], 0x80
	v_writelane_b32 v254, s61, 56
	v_writelane_b32 v254, s62, 57
	s_barrier
	s_nop 0
	v_writelane_b32 v254, s63, 58
	v_writelane_b32 v254, s64, 59
	s_nop 1
	v_writelane_b32 v254, s65, 60
	v_writelane_b32 v254, s49, 61
	v_writelane_b32 v254, s55, 62
	s_branch .LBB0_80

;     __device__ __forceinline__ const float* in(int i) const { return (const float*)(const __attribute__((address_space(1))) float*)ld(i); }
;     __device__ __forceinline__ unsigned char* ws() const { return (unsigned char*)(__attribute__((address_space(1))) unsigned char*)ld(23); }
; __device__ __forceinline__ void gla_prefetch(v4u& pz0, v4u& pz1, v4u& pw0, v4u& pw1, const KPD& kp, int l, int pair, int lane, int wave) {
;     const int half = wave >> 2, w4 = wave & 3, item = 2 * pair + half, h = item & 3, sc = item >> 2; int b, n, rowbase; chunk_coords(sc, b, n, rowbase);
;     const int dir = w4 >> 1, d0 = 24 * (w4 & 1);
;     const bf16* prow = (const bf16*)(kp.ws() + WS_P) + (size_t)(rowbase + lane) * INP;
;     pz0 = *(const v4u*)(prow + (dir ? C_ZB : C_ZF)); pz1 = *(const v4u*)(prow + (dir ? C_ZB : C_ZF) + 8);
;     const float* W = kp.in(I_GWDEC) + (size_t)((l * 2 + dir) * 16) * 192 + h * 48 + d0;
;     const float* bias = kp.in(I_GBDEC) + (l * 2 + dir) * 192 + h * 48 + d0;
;     unsigned w[6];
; #pragma unroll
;     for (int i = 0; i < 6; ++i) { const int e = lane + 64 * i; w[i] = __float_as_uint(W[(e / 24) * 192 + (e % 24)]); }
;     pw0 = (v4u){w[0], w[1], w[2], w[3]}; pw1 = (v4u){w[4], w[5], __float_as_uint(bias[lane < 24 ? lane : 0]), 0u};
; }
.LBB0_251:
	s_lshl_b32 s0, s4, 6
	s_and_b32 s1, s3, 3
	s_add_i32 s3, s5, s0
	s_lshr_b32 s0, s12, 1
	s_and_b32 s4, s0, 1
	s_and_b32 s6, 64, s2
	s_cmp_eq_u32 s4, 0
	s_movk_i32 s0, 0x920
	v_readlane_b32 s10, v254, 27
	s_cselect_b32 s0, 0x900, s0
	s_lshl_b32 s5, s10, 1
	s_or_b32 s9, s4, s5
	s_mul_i32 s78, s9, 0xc00
	s_waitcnt lgkmcnt(0)
	v_readlane_b32 s8, v255, 60
	s_lshl_b64 s[4:5], s[78:79], 2
	v_readlane_b32 s7, v255, 61
	s_add_u32 s4, s8, s4
	s_addc_u32 s5, s7, s5
	s_mul_i32 s7, s1, 0xc0
	s_add_u32 s8, s4, s7
	v_readlane_b32 s1, v255, 63
	v_readlane_b32 s4, v255, 62
	v_or_b32_e32 v2, s3, v120
	v_mov_b32_e32 v5, s1
	v_mov_b32_e32 v4, s4
	s_addc_u32 s10, s5, 0
	v_mad_i64_i32 v[4:5], s[4:5], v2, s33, v[4:5]
	s_mov_b32 s1, s79
	v_lshl_add_u64 v[4:5], v[4:5], 0, s[0:1]
	s_mov_b64 s[0:1], 0x7800000
	v_lshl_add_u64 v[6:7], v[4:5], 0, s[0:1]
	s_mov_b32 s0, 0x7800000
	v_add_co_u32_e32 v4, vcc, s0, v4
	s_cmp_lg_u32 s6, 0
	s_nop 0
	v_addc_co_u32_e32 v5, vcc, 0, v5, vcc
	global_load_dwordx4 v[18:21], v[4:5], off
	global_load_dwordx4 v[22:25], v[6:7], off offset:16
	ds_read_b64 v[4:5], v252
	v_mul_lo_u16_e32 v2, 43, v120
	v_or_b32_e32 v6, 64, v120
	v_or_b32_e32 v7, 0x80, v120
	v_or_b32_e32 v8, 0xc0, v120
	s_cselect_b32 s3, 0x60, 0
	v_lshrrev_b16_e32 v2, 10, v2
	v_mul_lo_u16_e32 v6, 43, v6
	v_mul_lo_u16_e32 v7, 0xab, v7
	v_mul_lo_u16_e32 v8, 0xab, v8
	v_or_b32_e32 v9, 0x100, v120
	v_or_b32_e32 v10, 0x140, v120
	s_add_u32 s0, s8, s3
	v_mul_u32_u24_e32 v2, 0xa8, v2
	v_lshrrev_b16_e32 v6, 10, v6
	v_lshrrev_b16_e32 v7, 12, v7
	v_lshrrev_b16_e32 v8, 12, v8
	v_mul_u32_u24_e32 v9, 0xaab, v9
	s_movk_i32 s4, 0xa8
	v_mul_u32_u24_e32 v10, 0xaab, v10
	s_addc_u32 s1, s10, 0
	v_add_lshl_u32 v2, v2, v120, 2
	v_mul_u32_u24_e32 v6, 0xa8, v6
	v_mul_u32_u24_e32 v7, 0xa8, v7
	v_mul_u32_u24_e32 v8, 0xa8, v8
	v_mul_lo_u16_sdwa v9, v9, s4 dst_sel:DWORD dst_unused:UNUSED_PAD src0_sel:WORD_1 src1_sel:DWORD
	v_mul_lo_u16_sdwa v10, v10, s4 dst_sel:DWORD dst_unused:UNUSED_PAD src0_sel:WORD_1 src1_sel:DWORD
	s_mul_i32 s78, s9, 0xc0
	v_add_lshl_u32 v6, v6, v120, 2
	v_add_lshl_u32 v7, v7, v120, 2
	v_add_lshl_u32 v8, v8, v120, 2
	v_add_lshl_u32 v9, v120, v9, 2
	v_add_lshl_u32 v10, v120, v10, 2
	global_load_dword v26, v2, s[0:1]
	global_load_dword v27, v6, s[0:1] offset:256
	global_load_dword v28, v7, s[0:1] offset:512
	global_load_dword v29, v8, s[0:1] offset:768
	global_load_dword v30, v9, s[0:1] offset:1024
	global_load_dword v31, v10, s[0:1] offset:1280
	s_waitcnt lgkmcnt(0)
	v_readfirstlane_b32 s5, v4
	s_lshl_b64 s[0:1], s[78:79], 2
	v_readfirstlane_b32 s4, v5
	s_add_u32 s0, s5, s0
	s_addc_u32 s1, s4, s1
	s_add_u32 s0, s0, s7
	s_addc_u32 s1, s1, 0
	v_cmp_gt_u32_e32 vcc, 24, v120
	s_add_u32 s0, s0, s3
	s_addc_u32 s1, s1, 0
	v_cndmask_b32_e32 v2, 0, v120, vcc
	v_lshlrev_b32_e32 v2, 2, v2
	global_load_dword v32, v2, s[0:1]
	v_readlane_b32 s11, v254, 28
	s_branch .LBB0_253

;     __device__ __forceinline__ const float* in(int i) const { return (const float*)(const __attribute__((address_space(1))) float*)ld(i); }
;     __device__ __forceinline__ unsigned char* ws() const { return (unsigned char*)(__attribute__((address_space(1))) unsigned char*)ld(23); }
; __device__ __forceinline__ void gla_prefetch(v4u& pz0, v4u& pz1, v4u& pw0, v4u& pw1, const KPD& kp, int l, int pair, int lane, int wave) {
;     const int half = wave >> 2, w4 = wave & 3, item = 2 * pair + half, h = item & 3, sc = item >> 2; int b, n, rowbase; chunk_coords(sc, b, n, rowbase);
;     const int dir = w4 >> 1, d0 = 24 * (w4 & 1);
;     const bf16* prow = (const bf16*)(kp.ws() + WS_P) + (size_t)(rowbase + lane) * INP;
;     pz0 = *(const v4u*)(prow + (dir ? C_ZB : C_ZF)); pz1 = *(const v4u*)(prow + (dir ? C_ZB : C_ZF) + 8);
;     const float* W = kp.in(I_GWDEC) + (size_t)((l * 2 + dir) * 16) * 192 + h * 48 + d0;
;     const float* bias = kp.in(I_GBDEC) + (l * 2 + dir) * 192 + h * 48 + d0;
;     unsigned w[6];
; #pragma unroll
;     for (int i = 0; i < 6; ++i) { const int e = lane + 64 * i; w[i] = __float_as_uint(W[(e / 24) * 192 + (e % 24)]); }
;     pw0 = (v4u){w[0], w[1], w[2], w[3]}; pw1 = (v4u){w[4], w[5], __float_as_uint(bias[lane < 24 ? lane : 0]), 0u};
; }
.LBB0_271:
	s_lshl_b32 s10, s13, 6
	s_add_i32 s10, s17, s10
	v_or_b32_e32 v4, s10, v120
	s_mov_b32 s17, s79
	s_waitcnt lgkmcnt(0)
	v_readlane_b32 s11, v255, 63
	v_readlane_b32 s13, v255, 62
	s_nop 0
	v_mov_b32_e32 v3, s11
	v_mov_b32_e32 v2, s13
	v_mad_i64_i32 v[2:3], s[10:11], v4, s33, v[2:3]
	v_lshl_add_u64 v[2:3], v[2:3], 0, s[16:17]
	s_mov_b64 s[10:11], 0x7800000
	v_lshl_add_u64 v[4:5], v[2:3], 0, s[10:11]
	s_mov_b32 s10, 0x7800000
	v_add_co_u32_e32 v2, vcc, s10, v2
	s_and_b32 s10, s12, 3
	s_nop 0
	v_addc_co_u32_e32 v3, vcc, 0, v3, vcc
	global_load_dwordx4 v[18:21], v[2:3], off
	global_load_dwordx4 v[22:25], v[4:5], off offset:16
	s_mul_i32 s13, s10, 0xc0
	s_waitcnt lgkmcnt(0)
	v_readlane_b32 s12, v255, 60
	v_readlane_b32 s11, v255, 61
	s_add_u32 s12, s12, s18
	s_addc_u32 s11, s11, s19
	ds_read_b64 v[2:3], v252
	s_add_u32 s10, s12, s13
	s_addc_u32 s11, s11, 0
	s_add_u32 s10, s10, s42
	s_addc_u32 s11, s11, 0
	global_load_dword v26, v142, s[10:11]
	global_load_dword v27, v143, s[10:11] offset:256
	global_load_dword v28, v144, s[10:11] offset:512
	global_load_dword v29, v145, s[10:11] offset:768
	global_load_dword v30, v146, s[10:11] offset:1024
	global_load_dword v31, v147, s[10:11] offset:1280
	s_waitcnt lgkmcnt(0)
	v_readfirstlane_b32 s11, v2
	v_readfirstlane_b32 s10, v3
	s_add_u32 s11, s11, s20
	s_addc_u32 s10, s10, s21
	s_add_u32 s11, s11, s13
	s_addc_u32 s12, s10, 0
	s_add_u32 s10, s11, s42
	s_addc_u32 s11, s12, 0
	global_load_dword v32, v148, s[10:11]

; __device__ __forceinline__ void swa_item(const KPD& kp, int l, int item, unsigned char* lds, int tid, int lane, int wave) {
;     const bool isctx = item >= 512;
;     int b, qblk, kvh, qrow0;
;     if (!isctx) { kvh = item & 1; qblk = (item >> 1) & 63; b = item >> 7; qrow0 = b * SEQ + qblk * 128; }
;     else { const int j = item - 512; kvh = j & 1; qblk = (j >> 1) & 1; b = j >> 2; qrow0 = MLAT + b * CTXL + qblk * 128; }
;     const bf16* P = (const bf16*)(kp.ws() + WS_P);
;     bf16* Kt = (bf16*)lds;
;     bf16* Vs = (bf16*)(lds + 18432);
;     const int fr = lane & 15, fq = lane >> 4;
;     bf16x8 qf[3][2];
; #pragma unroll
;     for (int hh = 0; hh < 3; ++hh)
; #pragma unroll
;         for (int ks = 0; ks < 2; ++ks) qf[hh][ks] = *(const bf16x8*)(P + (size_t)(qrow0 + 16 * wave + fr) * INP + C_AQ + (kvh * 3 + hh) * 64 + 32 * ks + 8 * fq);
;     float mrow[3], lrow[3]; f32x4 O[3][4];
; #pragma unroll
;     for (int hh = 0; hh < 3; ++hh) { mrow[hh] = kp.in(I_SINK)[l * 6 + kvh * 3 + hh] * 1.4426950408889634f; lrow[hh] = (fq == 0) ? 1.f : 0.f;
; #pragma unroll
;         for (int dt = 0; dt < 4; ++dt) O[hh][dt] = (f32x4){0.f, 0.f, 0.f, 0.f}; }
;     int nt = 0; int krow[5]; int kmode[5];
; #pragma unroll
;     for (int kt = 0; kt < 5; ++kt) { krow[kt] = 0; kmode[kt] = 0; }
;     int t0 = 0;
;     if (!isctx) {
;         if (qblk > 0) { krow[0] = b * SEQ + (qblk - 1) * 128; kmode[0] = 1; t0 = 1; }
;     }
;     const bool hasprev = !isctx && qblk > 0, hascur = !isctx, hasnext = !isctx && qblk < 63;
;     const int s_prev = 0, s_next = hasprev ? 1 : 0, s_cur = s_next + (hasnext ? 1 : 0), s_c0 = s_cur + (hascur ? 1 : 0), s_c1 = s_c0 + 1;
;     nt = s_c1 + 1;
;     (void)t0; (void)s_prev;
;     auto tile_row = [&](int i) -> int {
;         if (hasprev && i == 0) return b * SEQ + (qblk - 1) * 128;
;         if (hasnext && i == s_next) return b * SEQ + (qblk + 1) * 128;
;         if (hascur && i == s_cur) return b * SEQ + qblk * 128;
;         if (i == s_c0) return MLAT + b * CTXL;
;         return MLAT + b * CTXL + 128; };
;     auto tile_mode = [&](int i) -> int { if (hasprev && i == 0) return 1; if (hasnext && i == s_next) return 2; return 0; };
;     v4u kpre[4], vpre2[4];
;     const int nstage = (nt + 1) >> 1;
;     ...
;     SWA_LOAD_STAGE(0);
.LBB0_363:
	s_and_b32 s21, s8, 1
	v_add_u32_e32 v168, s9, v174
	v_readlane_b32 s10, v254, 27
	v_readlane_b32 s11, v254, 28
	s_waitcnt lgkmcnt(0)
	v_readlane_b32 s4, v255, 62
	v_readlane_b32 s5, v255, 63
	s_add_u32 s4, s4, 0x7800000
	s_addc_u32 s5, s5, 0
	v_mov_b64_e32 v[2:3], s[4:5]
	v_mad_i64_i32 v[2:3], s[8:9], v168, s33, v[2:3]
	s_mul_i32 s8, s21, 0xc0
	v_lshl_add_u64 v[2:3], v[2:3], 0, v[34:35]
	s_lshl_b32 s78, s8, 1
	s_waitcnt vmcnt(7)
	v_lshl_add_u64 v[22:23], v[2:3], 0, s[78:79]
	global_load_dwordx4 v[2:5], v[22:23], off offset:2368
	global_load_dwordx4 v[6:9], v[22:23], off offset:2432
	global_load_dwordx4 v[10:13], v[22:23], off offset:2496
	global_load_dwordx4 v[14:17], v[22:23], off offset:2560
	global_load_dwordx4 v[18:21], v[22:23], off offset:2624
	s_nop 0
	global_load_dwordx4 v[22:25], v[22:23], off offset:2688
	s_waitcnt vmcnt(11)
	s_mul_i32 s8, s21, 3
	s_mul_i32 s9, s10, 6
	s_add_i32 s8, s8, s9
	s_mov_b32 s9, s79
	s_waitcnt lgkmcnt(0)
	v_readlane_b32 s10, v255, 56
	s_lshl_b64 s[8:9], s[8:9], 2
	v_readlane_b32 s11, v255, 57
	s_add_u32 s10, s10, s8
	s_addc_u32 s11, s11, s9
	v_mov_b32_e32 v167, v35
	s_nop 1
	global_load_dword v68, v35, s[10:11]
	s_waitcnt lgkmcnt(0)
	v_readlane_b32 s10, v255, 56
	v_readlane_b32 s11, v255, 57
	s_add_u32 s10, s10, s8
	s_addc_u32 s11, s11, s9
	s_nop 2
	global_load_dword v67, v35, s[10:11] offset:4
	s_waitcnt lgkmcnt(0)
	v_readlane_b32 s11, v255, 56
	v_readlane_b32 s10, v255, 57
	s_add_u32 s8, s11, s8
	s_addc_u32 s9, s10, s9
	s_cmp_lg_u32 s12, 0
	global_load_dword v66, v35, s[8:9] offset:8
	s_cselect_b64 s[8:9], -1, 0
	s_and_b64 s[8:9], s[6:7], s[8:9]
	s_cmp_lg_u32 s12, 63
	s_cselect_b64 s[10:11], -1, 0
	v_cndmask_b32_e64 v26, 0, 1, s[8:9]
	s_and_b64 s[10:11], s[6:7], s[10:11]
	v_readfirstlane_b32 s17, v26
	v_cndmask_b32_e64 v26, 0, 1, s[10:11]
	s_lshl_b32 s21, s21, 7
	v_readfirstlane_b32 s18, v26
	v_cndmask_b32_e64 v26, 0, 1, s[6:7]
	s_add_i32 s18, s17, s18
	v_readfirstlane_b32 s19, v26
	s_add_i32 s19, s18, s19
	s_add_u32 s4, s4, s21
	s_addc_u32 s5, s5, 0
	v_lshl_add_u64 v[170:171], s[4:5], 0, v[166:167]
	s_add_i32 s4, s20, s13
	s_add_i32 s13, s4, 0x80
	s_add_i32 s20, s4, 0xffffff80
	s_and_b64 s[4:5], s[8:9], exec
	s_cselect_b32 s20, s20, s13
	s_cmp_eq_u32 s19, 0
	s_cselect_b32 s4, 0x8000, s68
	s_add_i32 s21, s4, s15
	s_and_b64 s[4:5], s[6:7], exec
	s_cselect_b32 s20, s20, s21
	v_add_u32_e32 v26, s20, v176
	v_add_u32_e32 v38, s20, v177
	s_waitcnt vmcnt(10)
	v_mad_i64_i32 v[30:31], s[4:5], v26, s33, v[170:171]
	v_mad_i64_i32 v[46:47], s[4:5], v38, s33, v[170:171]
	global_load_dwordx4 v[26:29], v[30:31], off offset:3136
	s_nop 0
	global_load_dwordx4 v[30:33], v[30:31], off offset:3392
	s_nop 0
	global_load_dwordx4 v[42:45], v[46:47], off offset:3136
	s_nop 0
	global_load_dwordx4 v[46:49], v[46:47], off offset:3392
	s_andn2_b64 vcc, exec, s[6:7]
	s_mov_b64 s[4:5], -1
	s_cbranch_vccnz .LBB0_366
	s_cmp_gt_i32 s12, 62
	s_cbranch_scc1 .LBB0_366
	s_cmp_eq_u32 s12, 0
	s_cselect_b64 s[4:5], -1, 0

;     __device__ __forceinline__ const float* in(int i) const { return (const float*)(const __attribute__((address_space(1))) float*)ld(i); }
;     __device__ __forceinline__ unsigned char* ws() const { return (unsigned char*)(__attribute__((address_space(1))) unsigned char*)ld(23); }
; __device__ __forceinline__ void gla_prefetch(v4u& pz0, v4u& pz1, v4u& pw0, v4u& pw1, const KPD& kp, int l, int pair, int lane, int wave) {
;     const int half = wave >> 2, w4 = wave & 3, item = 2 * pair + half, h = item & 3, sc = item >> 2; int b, n, rowbase; chunk_coords(sc, b, n, rowbase);
;     const int dir = w4 >> 1, d0 = 24 * (w4 & 1);
;     const bf16* prow = (const bf16*)(kp.ws() + WS_P) + (size_t)(rowbase + lane) * INP;
;     pz0 = *(const v4u*)(prow + (dir ? C_ZB : C_ZF)); pz1 = *(const v4u*)(prow + (dir ? C_ZB : C_ZF) + 8);
;     const float* W = kp.in(I_GWDEC) + (size_t)((l * 2 + dir) * 16) * 192 + h * 48 + d0;
;     const float* bias = kp.in(I_GBDEC) + (l * 2 + dir) * 192 + h * 48 + d0;
;     unsigned w[6];
; #pragma unroll
;     for (int i = 0; i < 6; ++i) { const int e = lane + 64 * i; w[i] = __float_as_uint(W[(e / 24) * 192 + (e % 24)]); }
;     pw0 = (v4u){w[0], w[1], w[2], w[3]}; pw1 = (v4u){w[4], w[5], __float_as_uint(bias[lane < 24 ? lane : 0]), 0u};
; }
.LBB0_450:
	s_lshl_b32 s0, s4, 6
	s_and_b32 s1, s3, 3
	s_add_i32 s3, s5, s0
	s_lshr_b32 s0, s13, 1
	s_and_b32 s4, s0, 1
	s_and_b32 s6, 64, s2
	s_cmp_eq_u32 s4, 0
	s_movk_i32 s0, 0x920
	v_readlane_b32 s10, v254, 27
	s_cselect_b32 s0, 0x900, s0
	s_lshl_b32 s5, s10, 1
	s_or_b32 s9, s4, s5
	s_mul_i32 s78, s9, 0xc00
	s_waitcnt lgkmcnt(0)
	v_readlane_b32 s8, v255, 60
	s_lshl_b64 s[4:5], s[78:79], 2
	v_readlane_b32 s7, v255, 61
	s_add_u32 s4, s8, s4
	s_addc_u32 s5, s7, s5
	s_mul_i32 s7, s1, 0xc0
	s_add_u32 s8, s4, s7
	v_readlane_b32 s1, v255, 63
	v_readlane_b32 s4, v255, 62
	v_or_b32_e32 v4, s3, v80
	v_mov_b32_e32 v3, s1
	v_mov_b32_e32 v2, s4
	s_addc_u32 s10, s5, 0
	v_mad_i64_i32 v[2:3], s[4:5], v4, s33, v[2:3]
	s_mov_b32 s1, s79
	v_lshl_add_u64 v[2:3], v[2:3], 0, s[0:1]
	s_mov_b64 s[0:1], 0x7800000
	v_lshl_add_u64 v[4:5], v[2:3], 0, s[0:1]
	s_mov_b32 s0, 0x7800000
	v_add_co_u32_e32 v2, vcc, s0, v2
	s_cmp_lg_u32 s6, 0
	s_nop 0
	v_addc_co_u32_e32 v3, vcc, 0, v3, vcc
	global_load_dwordx4 v[42:45], v[2:3], off
	global_load_dwordx4 v[46:49], v[4:5], off offset:16
	ds_read_b64 v[2:3], v252
	v_mul_lo_u16_e32 v4, 43, v80
	v_or_b32_e32 v5, 64, v80
	v_or_b32_e32 v6, 0x80, v80
	v_or_b32_e32 v7, 0xc0, v80
	s_cselect_b32 s3, 0x60, 0
	v_lshrrev_b16_e32 v4, 10, v4
	v_mul_lo_u16_e32 v5, 43, v5
	v_mul_lo_u16_e32 v6, 0xab, v6
	v_mul_lo_u16_e32 v7, 0xab, v7
	v_or_b32_e32 v8, 0x100, v80
	v_or_b32_e32 v9, 0x140, v80
	s_add_u32 s0, s8, s3
	v_mul_u32_u24_e32 v4, 0xa8, v4
	v_lshrrev_b16_e32 v5, 10, v5
	v_lshrrev_b16_e32 v6, 12, v6
	v_lshrrev_b16_e32 v7, 12, v7
	v_mul_u32_u24_e32 v8, 0xaab, v8
	s_movk_i32 s4, 0xa8
	v_mul_u32_u24_e32 v9, 0xaab, v9
	s_addc_u32 s1, s10, 0
	v_add_lshl_u32 v4, v4, v80, 2
	v_mul_u32_u24_e32 v5, 0xa8, v5
	v_mul_u32_u24_e32 v6, 0xa8, v6
	v_mul_u32_u24_e32 v7, 0xa8, v7
	v_mul_lo_u16_sdwa v8, v8, s4 dst_sel:DWORD dst_unused:UNUSED_PAD src0_sel:WORD_1 src1_sel:DWORD
	v_mul_lo_u16_sdwa v9, v9, s4 dst_sel:DWORD dst_unused:UNUSED_PAD src0_sel:WORD_1 src1_sel:DWORD
	s_mul_i32 s78, s9, 0xc0
	v_add_lshl_u32 v5, v5, v80, 2
	v_add_lshl_u32 v6, v6, v80, 2
	v_add_lshl_u32 v7, v7, v80, 2
	v_add_lshl_u32 v8, v80, v8, 2
	v_add_lshl_u32 v9, v80, v9, 2
	global_load_dword v84, v4, s[0:1]
	global_load_dword v85, v5, s[0:1] offset:256
	global_load_dword v86, v6, s[0:1] offset:512
	global_load_dword v83, v7, s[0:1] offset:768
	global_load_dword v87, v8, s[0:1] offset:1024
	global_load_dword v88, v9, s[0:1] offset:1280
	s_waitcnt lgkmcnt(0)
	v_readfirstlane_b32 s5, v2
	s_lshl_b64 s[0:1], s[78:79], 2
	v_readfirstlane_b32 s4, v3
	s_add_u32 s0, s5, s0
	s_addc_u32 s1, s4, s1
	s_add_u32 s0, s0, s7
	s_addc_u32 s1, s1, 0
	v_cmp_gt_u32_e32 vcc, 24, v80
	s_add_u32 s0, s0, s3
	s_addc_u32 s1, s1, 0
	v_cndmask_b32_e32 v2, 0, v80, vcc
	v_lshlrev_b32_e32 v2, 2, v2
	global_load_dword v91, v2, s[0:1]
	v_readlane_b32 s11, v254, 28
	s_add_i32 s88, s87, 0xff
	s_cmp_ge_i32 s73, s88
	s_cbranch_scc0 .LBB0_452
	s_branch .LBB0_467

;     __device__ __forceinline__ const float* in(int i) const { return (const float*)(const __attribute__((address_space(1))) float*)ld(i); }
;     __device__ __forceinline__ unsigned char* ws() const { return (unsigned char*)(__attribute__((address_space(1))) unsigned char*)ld(23); }
; __device__ __forceinline__ void gla_prefetch(v4u& pz0, v4u& pz1, v4u& pw0, v4u& pw1, const KPD& kp, int l, int pair, int lane, int wave) {
;     const int half = wave >> 2, w4 = wave & 3, item = 2 * pair + half, h = item & 3, sc = item >> 2; int b, n, rowbase; chunk_coords(sc, b, n, rowbase);
;     const int dir = w4 >> 1, d0 = 24 * (w4 & 1);
;     const bf16* prow = (const bf16*)(kp.ws() + WS_P) + (size_t)(rowbase + lane) * INP;
;     pz0 = *(const v4u*)(prow + (dir ? C_ZB : C_ZF)); pz1 = *(const v4u*)(prow + (dir ? C_ZB : C_ZF) + 8);
;     const float* W = kp.in(I_GWDEC) + (size_t)((l * 2 + dir) * 16) * 192 + h * 48 + d0;
;     const float* bias = kp.in(I_GBDEC) + (l * 2 + dir) * 192 + h * 48 + d0;
;     unsigned w[6];
; #pragma unroll
;     for (int i = 0; i < 6; ++i) { const int e = lane + 64 * i; w[i] = __float_as_uint(W[(e / 24) * 192 + (e % 24)]); }
;     pw0 = (v4u){w[0], w[1], w[2], w[3]}; pw1 = (v4u){w[4], w[5], __float_as_uint(bias[lane < 24 ? lane : 0]), 0u};
; }
.LBB0_464:
	s_lshl_b32 s0, s3, 6
	s_add_i32 s0, s8, s0
	v_or_b32_e32 v4, s0, v80
	s_mov_b32 s77, s79
	s_waitcnt lgkmcnt(0)
	v_readlane_b32 s1, v255, 63
	v_readlane_b32 s3, v255, 62
	s_nop 0
	v_mov_b32_e32 v3, s1
	v_mov_b32_e32 v2, s3
	v_mad_i64_i32 v[2:3], s[0:1], v4, s33, v[2:3]
	v_lshl_add_u64 v[2:3], v[2:3], 0, s[76:77]
	s_mov_b64 s[0:1], 0x7800000
	v_lshl_add_u64 v[4:5], v[2:3], 0, s[0:1]
	s_mov_b32 s0, 0x7800000
	v_add_co_u32_e32 v2, vcc, s0, v2
	s_and_b32 s0, s2, 3
	s_nop 0
	v_addc_co_u32_e32 v3, vcc, 0, v3, vcc
	global_load_dwordx4 v[42:45], v[2:3], off
	global_load_dwordx4 v[46:49], v[4:5], off offset:16
	s_mul_i32 s3, s0, 0xc0
	s_waitcnt lgkmcnt(0)
	v_readlane_b32 s2, v255, 60
	v_readlane_b32 s1, v255, 61
	s_add_u32 s2, s2, s94
	s_addc_u32 s1, s1, s95
	ds_read_b64 v[2:3], v252
	s_add_u32 s0, s2, s3
	s_addc_u32 s1, s1, 0
	s_add_u32 s0, s0, s86
	s_addc_u32 s1, s1, 0
	global_load_dword v84, v120, s[0:1]
	global_load_dword v85, v121, s[0:1] offset:256
	global_load_dword v86, v122, s[0:1] offset:512
	global_load_dword v83, v123, s[0:1] offset:768
	global_load_dword v87, v124, s[0:1] offset:1024
	global_load_dword v88, v125, s[0:1] offset:1280
	s_waitcnt lgkmcnt(0)
	v_readfirstlane_b32 s1, v2
	v_readfirstlane_b32 s0, v3
	s_add_u32 s1, s1, s90
	s_addc_u32 s0, s0, s91
	s_add_u32 s1, s1, s3
	s_addc_u32 s2, s0, 0
	s_add_u32 s0, s1, s86
	s_addc_u32 s1, s2, 0
	global_load_dword v91, v126, s[0:1]

; __device__ __forceinline__ void swa_item(const KPD& kp, int l, int item, unsigned char* lds, int tid, int lane, int wave) {
;     const bool isctx = item >= 512;
;     int b, qblk, kvh, qrow0;
;     if (!isctx) { kvh = item & 1; qblk = (item >> 1) & 63; b = item >> 7; qrow0 = b * SEQ + qblk * 128; }
;     else { const int j = item - 512; kvh = j & 1; qblk = (j >> 1) & 1; b = j >> 2; qrow0 = MLAT + b * CTXL + qblk * 128; }
;     const bf16* P = (const bf16*)(kp.ws() + WS_P);
;     bf16* Kt = (bf16*)lds;
;     bf16* Vs = (bf16*)(lds + 18432);
;     const int fr = lane & 15, fq = lane >> 4;
;     bf16x8 qf[3][2];
; #pragma unroll
;     for (int hh = 0; hh < 3; ++hh)
; #pragma unroll
;         for (int ks = 0; ks < 2; ++ks) qf[hh][ks] = *(const bf16x8*)(P + (size_t)(qrow0 + 16 * wave + fr) * INP + C_AQ + (kvh * 3 + hh) * 64 + 32 * ks + 8 * fq);
;     float mrow[3], lrow[3]; f32x4 O[3][4];
; #pragma unroll
;     for (int hh = 0; hh < 3; ++hh) { mrow[hh] = kp.in(I_SINK)[l * 6 + kvh * 3 + hh] * 1.4426950408889634f; lrow[hh] = (fq == 0) ? 1.f : 0.f;
; #pragma unroll
;         for (int dt = 0; dt < 4; ++dt) O[hh][dt] = (f32x4){0.f, 0.f, 0.f, 0.f}; }
;     int nt = 0; int krow[5]; int kmode[5];
; #pragma unroll
;     for (int kt = 0; kt < 5; ++kt) { krow[kt] = 0; kmode[kt] = 0; }
;     int t0 = 0;
;     if (!isctx) {
;         if (qblk > 0) { krow[0] = b * SEQ + (qblk - 1) * 128; kmode[0] = 1; t0 = 1; }
;     }
;     const bool hasprev = !isctx && qblk > 0, hascur = !isctx, hasnext = !isctx && qblk < 63;
;     const int s_prev = 0, s_next = hasprev ? 1 : 0, s_cur = s_next + (hasnext ? 1 : 0), s_c0 = s_cur + (hascur ? 1 : 0), s_c1 = s_c0 + 1;
;     nt = s_c1 + 1;
;     (void)t0; (void)s_prev;
;     auto tile_row = [&](int i) -> int {
;         if (hasprev && i == 0) return b * SEQ + (qblk - 1) * 128;
;         if (hasnext && i == s_next) return b * SEQ + (qblk + 1) * 128;
;         if (hascur && i == s_cur) return b * SEQ + qblk * 128;
;         if (i == s_c0) return MLAT + b * CTXL;
;         return MLAT + b * CTXL + 128; };
;     auto tile_mode = [&](int i) -> int { if (hasprev && i == 0) return 1; if (hasnext && i == s_next) return 2; return 0; };
;     v4u kpre[4], vpre2[4];
;     const int nstage = (nt + 1) >> 1;
;     ...
;     SWA_LOAD_STAGE(0);
;     const int q4 = (lane & 15) >> 2, p4 = lane & 3;
; #pragma unroll 1
;     for (int st = 0; st < nstage; ++st) {
.LBB0_467:
	v_readlane_b32 s0, v253, 20
	v_readlane_b32 s1, v253, 21
	s_and_b64 s[0:1], s[46:47], s[0:1]
	s_andn2_b64 vcc, exec, s[0:1]
	s_movk_i32 s87, 0x3000
	s_mov_b32 s88, 0xf800000
	s_cbranch_vccnz .LBB0_477
	v_and_b32_e32 v134, 15, v81
	v_readlane_b32 s2, v253, 22
	v_and_b32_e32 v34, 48, v80
	v_readlane_b32 s4, v254, 22
	s_waitcnt lgkmcnt(0)
	v_readlane_b32 s0, v255, 62
	v_readlane_b32 s1, v255, 63
	s_add_u32 s0, s0, 0x7800000
	s_addc_u32 s1, s1, 0
	v_or_b32_e32 v2, s2, v134
	v_lshl_add_u32 v130, s13, 4, v2
	v_mov_b64_e32 v[2:3], s[0:1]
	v_mad_i64_i32 v[2:3], s[2:3], v130, s33, v[2:3]
	v_readlane_b32 s2, v254, 15
	v_lshl_add_u64 v[2:3], v[2:3], 0, v[34:35]
	s_lshl_b32 s78, s2, 1
	s_waitcnt vmcnt(7)
	v_lshl_add_u64 v[22:23], v[2:3], 0, s[78:79]
	global_load_dwordx4 v[2:5], v[22:23], off offset:2368
	global_load_dwordx4 v[6:9], v[22:23], off offset:2432
	global_load_dwordx4 v[10:13], v[22:23], off offset:2496
	global_load_dwordx4 v[14:17], v[22:23], off offset:2560
	global_load_dwordx4 v[18:21], v[22:23], off offset:2624
	s_nop 0
	global_load_dwordx4 v[22:25], v[22:23], off offset:2688
	s_waitcnt vmcnt(11)
	s_waitcnt vmcnt(8)
	v_mov_b32_e32 v30, s4
	v_add_u32_e32 v39, 0x200, v81
	v_ashrrev_i32_e32 v38, 3, v81
	v_ashrrev_i32_e32 v39, 3, v39
	s_waitcnt lgkmcnt(0)
	v_readlane_b32 s3, v255, 57
	v_readlane_b32 s2, v255, 56
	v_cmp_gt_u32_e32 vcc, 16, v80
	v_ashrrev_i32_e32 v131, 31, v130
	s_nop 0
	v_cndmask_b32_e64 v135, 0, 1.0, vcc
	s_nop 0
	global_load_dword v26, v30, s[2:3]
	s_waitcnt vmcnt(0)
	v_mul_f32_e32 v136, 0x3fb8aa3b, v26
	s_waitcnt lgkmcnt(0)
	v_readlane_b32 s3, v255, 57
	v_readlane_b32 s2, v255, 56
	s_nop 4
	global_load_dword v26, v30, s[2:3] offset:4
	s_waitcnt lgkmcnt(0)
	v_readlane_b32 s3, v255, 57
	v_readlane_b32 s2, v255, 56
	s_nop 4
	global_load_dword v27, v30, s[2:3] offset:8
	s_mov_b32 s2, 0x3fb8aa3b
	s_waitcnt vmcnt(0)
	v_pk_mul_f32 v[132:133], v[26:27], s[2:3] op_sel_hi:[1,0]
	v_readlane_b32 s2, v254, 23
	s_add_u32 s0, s0, s2
	v_lshlrev_b32_e32 v26, 4, v81
	s_addc_u32 s1, s1, 0
	v_and_b32_e32 v34, 0x70, v26
	v_readlane_b32 s2, v253, 23
	v_lshl_add_u64 v[36:37], s[0:1], 0, v[34:35]
	v_add_u32_e32 v34, 0, v34
	v_add_u32_e32 v26, s2, v38
	v_add_u32_e32 v40, s2, v39
	v_readlane_b32 s2, v253, 24
	v_mad_i64_i32 v[46:47], s[0:1], v40, s33, v[36:37]
	s_nop 0
	v_add_u32_e32 v40, s2, v39
	v_mad_i64_i32 v[54:55], s[0:1], v40, s33, v[36:37]
	v_add_u32_e32 v40, s2, v38
	v_mad_i64_i32 v[30:31], s[0:1], v26, s33, v[36:37]
	v_mad_i64_i32 v[36:37], s[0:1], v40, s33, v[36:37]
	global_load_dwordx4 v[26:29], v[30:31], off offset:3136
	s_nop 0
	global_load_dwordx4 v[30:33], v[30:31], off offset:3392
	s_nop 0
	global_load_dwordx4 v[42:45], v[46:47], off offset:3136
	s_nop 0
	global_load_dwordx4 v[46:49], v[46:47], off offset:3392
	s_nop 0
	global_load_dwordx4 v[50:53], v[54:55], off offset:3392
	s_nop 0
	global_load_dwordx4 v[54:57], v[54:55], off offset:3136
	s_nop 0
	global_load_dwordx4 v[58:61], v[36:37], off offset:3392
	global_load_dwordx4 v[62:65], v[36:37], off offset:3136
	v_and_b32_e32 v37, 48, v81
	v_add_u32_e32 v138, 0, v37
	v_lshrrev_b32_e32 v37, 2, v80
	v_bfe_u32 v36, v81, 2, 2
	v_and_b32_e32 v137, 12, v37
	v_or_b32_e32 v139, v36, v137
	v_lshlrev_b32_e32 v36, 3, v80
	v_and_b32_e32 v36, 24, v36
	s_movk_i32 s2, 0x90
	v_add_u32_e32 v140, 0, v36
	v_mad_u64_u32 v[36:37], s[0:1], v38, s2, v[34:35]
	v_mad_u64_u32 v[66:67], s[0:1], v39, s2, v[34:35]
	s_barrier
	v_mov_b32_e32 v34, v35
	v_mov_b32_e32 v37, v35
	s_mov_b32 s0, 0
	s_mov_b32 s1, 0
	s_waitcnt vmcnt(7)
	ds_write_b128 v36, v[26:29]
	s_waitcnt vmcnt(6)
	ds_write_b128 v36, v[30:33] offset:18432
	s_waitcnt vmcnt(5)
	ds_write_b128 v66, v[42:45]
	s_waitcnt vmcnt(4)
	ds_write_b128 v66, v[46:49] offset:18432
	s_waitcnt vmcnt(0)
	ds_write_b128 v36, v[62:65] offset:36864
	ds_write_b128 v36, v[58:61] offset:55296
	ds_write_b128 v66, v[54:57] offset:36864
	ds_write_b128 v66, v[50:53] offset:55296
	v_mov_b32_e32 v36, v35
	v_mov_b64_e32 v[26:27], v[34:35]
	v_mov_b64_e32 v[30:31], v[34:35]
	v_mov_b64_e32 v[48:49], v[36:37]
	v_mov_b64_e32 v[44:45], v[36:37]
	v_mov_b64_e32 v[52:53], v[36:37]
	v_mov_b64_e32 v[56:57], v[36:37]
	v_mov_b64_e32 v[64:65], v[36:37]
	v_mov_b64_e32 v[60:61], v[36:37]
	v_mov_b64_e32 v[68:69], v[36:37]
	v_mov_b64_e32 v[72:73], v[36:37]
	v_mov_b64_e32 v[80:81], v[36:37]
	v_mov_b64_e32 v[76:77], v[36:37]
	v_mov_b64_e32 v[28:29], v[36:37]
	v_mov_b64_e32 v[32:33], v[36:37]
	v_mov_b64_e32 v[46:47], v[34:35]
	v_mov_b64_e32 v[42:43], v[34:35]
	v_mov_b64_e32 v[50:51], v[34:35]
	v_mov_b64_e32 v[54:55], v[34:35]
	v_mov_b64_e32 v[62:63], v[34:35]
	v_mov_b64_e32 v[58:59], v[34:35]
	v_mov_b64_e32 v[66:67], v[34:35]
	v_mov_b64_e32 v[70:71], v[34:35]
	v_mov_b64_e32 v[78:79], v[34:35]
	v_mov_b64_e32 v[74:75], v[34:35]
	v_mov_b32_e32 v37, v135
	v_mov_b32_e32 v36, v135
	s_waitcnt lgkmcnt(0)
	s_barrier
	s_branch .LBB0_470
